# instruction selection: attention softmax uses one v_fma (s*log2e - m*log2e) instead of v_sub + v_mul before each exp (40 per unit)
# speedup vs baseline: 1.0043x; 1.0043x over previous
.LBB0_752:
	s_or_b64 exec, exec, s[70:71]
	s_ashr_i32 s70, s78, 11
	s_lshl_b32 vcc_lo, s70, 1
	s_and_b32 s69, s78, 0x7f
	s_bfm_b32 s71, vcc_lo, 0
	s_and_b32 s71, s71, s69
	s_bfe_u32 s79, s78, 0x40007
	s_lshr_b32 s72, s69, vcc_lo
	v_add_u32_e32 v2, s68, v138
	s_add_u32 s64, s50, s64
	v_ashrrev_i32_e32 v3, 31, v2
	s_addc_u32 s65, s51, s65
	v_lshlrev_b64 v[2:3], 7, v[2:3]
	v_lshl_add_u64 v[2:3], s[64:65], 0, v[2:3]
	v_mov_b32_e32 v131, v1
	v_lshl_add_u64 v[2:3], v[2:3], 0, v[130:131]
	global_load_dwordx4 v[80:83], v[2:3], off
	global_load_dwordx4 v[84:87], v[2:3], off offset:64
	ds_read_b128 v[216:219], v141 offset:36864
	ds_read_b128 v[220:223], v141 offset:36928
	ds_read_b128 v[224:227], v142 offset:36864
	ds_read_b128 v[228:231], v142 offset:36928
	ds_read_b128 v[232:235], v143 offset:36864
	ds_read_b128 v[236:239], v143 offset:36928
	ds_read_b128 v[240:243], v144 offset:36864
	ds_read_b128 v[244:247], v144 offset:36928
	ds_read_b128 v[182:185], v145 offset:36864
	ds_read_b128 v[186:189], v145 offset:36928
	ds_read_b128 v[190:193], v146 offset:36864
	ds_read_b128 v[194:197], v146 offset:36928
	ds_read_b128 v[160:163], v147 offset:36864
	ds_read_b128 v[198:201], v147 offset:36928
	s_waitcnt vmcnt(13) lgkmcnt(13)
	v_mfma_f32_16x16x32_bf16 v[152:155], v[216:219], v[88:91], 0
	v_lshl_add_u32 v0, s72, 7, v138
	s_cmp_lg_u32 s72, 0
	s_cselect_b32 s100, 0, 0x80
	v_lshrrev_b32_e32 v178, 6, v202
	v_and_b32_e32 v179, 15, v202
	v_lshl_or_b32 v178, v178, 4, v179
	v_lshrrev_b32_e32 v179, 7, v202
	v_bfe_u32 v180, v202, 4, 2
	v_lshlrev_b32_e32 v180, 2, v180
	v_lshl_add_u32 v179, v179, 5, v180
	v_max_u32_e32 v180, s100, v178
	v_sub_u32_e32 v175, v179, v180
	v_sub_u32_e32 v176, v178, v180
	v_add_u32_e32 v176, 0x81, v176
	v_lshlrev_b32_e32 v0, vcc_lo, v0
	s_waitcnt vmcnt(12) lgkmcnt(12)
	v_mfma_f32_16x16x32_bf16 v[152:155], v[220:223], v[92:95], v[152:155]
	ds_read_b128 v[216:219], v148 offset:36864
	ds_read_b128 v[220:223], v148 offset:36928
	s_waitcnt lgkmcnt(13)
	v_mfma_f32_16x16x32_bf16 v[124:127], v[224:227], v[88:91], 0
	s_waitcnt lgkmcnt(12)
	v_mfma_f32_16x16x32_bf16 v[124:127], v[228:231], v[92:95], v[124:127]
	ds_read_b128 v[224:227], v149 offset:36864
	ds_read_b128 v[228:231], v149 offset:36928
	s_waitcnt lgkmcnt(13)
	v_mfma_f32_16x16x32_bf16 v[120:123], v[232:235], v[88:91], 0
	s_waitcnt lgkmcnt(12)
	v_mfma_f32_16x16x32_bf16 v[120:123], v[236:239], v[92:95], v[120:123]
	ds_read_b128 v[232:235], v150 offset:36864
	ds_read_b128 v[236:239], v150 offset:36928
	s_waitcnt lgkmcnt(13)
	v_mfma_f32_16x16x32_bf16 v[116:119], v[240:243], v[88:91], 0
	s_waitcnt lgkmcnt(12)
	v_mfma_f32_16x16x32_bf16 v[116:119], v[244:247], v[92:95], v[116:119]
	s_waitcnt lgkmcnt(11)
	v_mfma_f32_16x16x32_bf16 v[112:115], v[182:185], v[88:91], 0
	s_waitcnt lgkmcnt(10)
	v_mfma_f32_16x16x32_bf16 v[112:115], v[186:189], v[92:95], v[112:115]
	s_waitcnt lgkmcnt(9)
	v_mfma_f32_16x16x32_bf16 v[108:111], v[190:193], v[88:91], 0
	s_waitcnt lgkmcnt(8)
	v_mfma_f32_16x16x32_bf16 v[108:111], v[194:197], v[92:95], v[108:111]
	s_waitcnt lgkmcnt(7)
	v_mfma_f32_16x16x32_bf16 v[104:107], v[160:163], v[88:91], 0
	s_waitcnt lgkmcnt(6)
	v_mfma_f32_16x16x32_bf16 v[104:107], v[198:201], v[92:95], v[104:107]
	s_waitcnt lgkmcnt(5)
	v_mfma_f32_16x16x32_bf16 v[100:103], v[216:219], v[88:91], 0
	s_waitcnt lgkmcnt(4)
	v_mfma_f32_16x16x32_bf16 v[100:103], v[220:223], v[92:95], v[100:103]
	s_waitcnt lgkmcnt(3)
	v_mfma_f32_16x16x32_bf16 v[96:99], v[224:227], v[88:91], 0
	s_waitcnt lgkmcnt(2)
	v_mfma_f32_16x16x32_bf16 v[96:99], v[228:231], v[92:95], v[96:99]
	s_waitcnt lgkmcnt(1)
	v_mfma_f32_16x16x32_bf16 v[88:91], v[232:235], v[88:91], 0
	s_waitcnt lgkmcnt(0)
	v_mfma_f32_16x16x32_bf16 v[88:91], v[236:239], v[92:95], v[88:91]
	s_mov_b32 s68, 0xff61b1e6
	v_add_u32_e32 v177, 0, v175
	v_cmp_lt_u32_e32 vcc, v177, v176
	s_nop 1
	v_cndmask_b32_e32 v3, v213, v152, vcc
	v_add_u32_e32 v177, 1, v175
	v_cmp_lt_u32_e32 vcc, v177, v176
	s_nop 1
	v_cndmask_b32_e32 v2, v213, v153, vcc
	v_max3_f32 v94, v3, s68, v2
	v_add_u32_e32 v177, 2, v175
	v_cmp_lt_u32_e32 vcc, v177, v176
	s_nop 1
	v_cndmask_b32_e32 v92, v213, v154, vcc
	v_add_u32_e32 v177, 3, v175
	v_cmp_lt_u32_e32 vcc, v177, v176
	s_nop 1
	v_cndmask_b32_e32 v93, v213, v155, vcc
	v_add_u32_e32 v177, 16, v175
	v_cmp_lt_u32_e32 vcc, v177, v176
	s_nop 1
	v_cndmask_b32_e32 v95, v213, v124, vcc
	v_max3_f32 v129, v94, v92, v93
	v_add_u32_e32 v177, 17, v175
	v_cmp_lt_u32_e32 vcc, v177, v176
	s_nop 1
	v_cndmask_b32_e32 v94, v213, v125, vcc
	v_add_u32_e32 v177, 18, v175
	v_cmp_lt_u32_e32 vcc, v177, v176
	s_nop 1
	v_cndmask_b32_e32 v124, v213, v126, vcc
	v_add_u32_e32 v177, 19, v175
	v_cmp_lt_u32_e32 vcc, v177, v176
	s_nop 1
	v_cndmask_b32_e32 v125, v213, v127, vcc
	v_add_u32_e32 v177, 32, v175
	v_cmp_lt_u32_e32 vcc, v177, v176
	s_nop 1
	v_cndmask_b32_e32 v126, v213, v120, vcc
	v_add_u32_e32 v177, 33, v175
	v_cmp_lt_u32_e32 vcc, v177, v176
	s_nop 1
	v_cndmask_b32_e32 v120, v213, v121, vcc
	v_add_u32_e32 v177, 34, v175
	v_cmp_lt_u32_e32 vcc, v177, v176
	s_nop 1
	v_cndmask_b32_e32 v121, v213, v122, vcc
	v_add_u32_e32 v177, 35, v175
	v_cmp_lt_u32_e32 vcc, v177, v176
	s_nop 1
	v_cndmask_b32_e32 v122, v213, v123, vcc
	v_add_u32_e32 v177, 48, v175
	v_cmp_lt_u32_e32 vcc, v177, v176
	s_nop 1
	v_cndmask_b32_e32 v123, v213, v116, vcc
	v_add_u32_e32 v177, 49, v175
	v_cmp_lt_u32_e32 vcc, v177, v176
	s_nop 1
	v_cndmask_b32_e32 v116, v213, v117, vcc
	v_add_u32_e32 v177, 50, v175
	v_cmp_lt_u32_e32 vcc, v177, v176
	s_nop 1
	v_cndmask_b32_e32 v117, v213, v118, vcc
	v_add_u32_e32 v177, 51, v175
	v_cmp_lt_u32_e32 vcc, v177, v176
	s_nop 1
	v_cndmask_b32_e32 v118, v213, v119, vcc
	v_add_u32_e32 v177, 64, v175
	v_cmp_lt_u32_e32 vcc, v177, v176
	s_nop 1
	v_cndmask_b32_e32 v119, v213, v112, vcc
	v_add_u32_e32 v177, 0x41, v175
	v_cmp_lt_u32_e32 vcc, v177, v176
	s_nop 1
	v_cndmask_b32_e32 v112, v213, v113, vcc
	v_add_u32_e32 v177, 0x42, v175
	v_cmp_lt_u32_e32 vcc, v177, v176
	s_nop 1
	v_cndmask_b32_e32 v113, v213, v114, vcc
	v_add_u32_e32 v177, 0x43, v175
	v_cmp_lt_u32_e32 vcc, v177, v176
	s_nop 1
	v_cndmask_b32_e32 v114, v213, v115, vcc
	v_add_u32_e32 v177, 0x50, v175
	v_cmp_lt_u32_e32 vcc, v177, v176
	s_nop 1
	v_cndmask_b32_e32 v115, v213, v108, vcc
	v_add_u32_e32 v177, 0x51, v175
	v_cmp_lt_u32_e32 vcc, v177, v176
	s_nop 1
	v_cndmask_b32_e32 v108, v213, v109, vcc
	v_add_u32_e32 v177, 0x52, v175
	v_cmp_lt_u32_e32 vcc, v177, v176
	s_nop 1
	v_cndmask_b32_e32 v109, v213, v110, vcc
	v_add_u32_e32 v177, 0x53, v175
	v_cmp_lt_u32_e32 vcc, v177, v176
	s_nop 1
	v_cndmask_b32_e32 v110, v213, v111, vcc
	v_max3_f32 v129, v129, v95, v94
	v_add_u32_e32 v177, 0x60, v175
	v_cmp_lt_u32_e32 vcc, v177, v176
	s_nop 1
	v_cndmask_b32_e32 v111, v213, v104, vcc
	v_max3_f32 v127, v129, v124, v125
	v_max3_f32 v127, v127, v126, v120
	v_add_u32_e32 v177, 0x61, v175
	v_cmp_lt_u32_e32 vcc, v177, v176
	s_nop 1
	v_cndmask_b32_e32 v104, v213, v105, vcc
	v_max3_f32 v127, v127, v121, v122
	v_max3_f32 v127, v127, v123, v116
	v_max3_f32 v127, v127, v117, v118
	v_add_u32_e32 v177, 0x62, v175
	v_cmp_lt_u32_e32 vcc, v177, v176
	s_nop 1
	v_cndmask_b32_e32 v105, v213, v106, vcc
	v_max3_f32 v127, v127, v119, v112
	v_max3_f32 v127, v127, v113, v114
	v_max3_f32 v127, v127, v115, v108
	v_add_u32_e32 v177, 0x63, v175
	v_cmp_lt_u32_e32 vcc, v177, v176
	s_nop 1
	v_cndmask_b32_e32 v107, v213, v107, vcc
	v_max3_f32 v127, v127, v109, v110
	v_max3_f32 v127, v127, v111, v104
	v_max3_f32 v106, v127, v105, v107
	v_add_u32_e32 v177, 0x70, v175
	v_cmp_lt_u32_e32 vcc, v177, v176
	s_nop 1
	v_cndmask_b32_e32 v127, v213, v100, vcc
	v_add_u32_e32 v177, 0x71, v175
	v_cmp_lt_u32_e32 vcc, v177, v176
	s_nop 1
	v_cndmask_b32_e32 v100, v213, v101, vcc
	v_add_u32_e32 v177, 0x72, v175
	v_cmp_lt_u32_e32 vcc, v177, v176
	s_nop 1
	v_cndmask_b32_e32 v101, v213, v102, vcc
	v_add_u32_e32 v177, 0x73, v175
	v_cmp_lt_u32_e32 vcc, v177, v176
	s_nop 1
	v_cndmask_b32_e32 v102, v213, v103, vcc
	v_add_u32_e32 v177, 0x80, v175
	v_cmp_lt_u32_e32 vcc, v177, v176
	s_nop 1
	v_cndmask_b32_e32 v103, v213, v96, vcc
	v_add_u32_e32 v177, 0x81, v175
	v_cmp_lt_u32_e32 vcc, v177, v176
	s_nop 1
	v_cndmask_b32_e32 v96, v213, v97, vcc
	v_add_u32_e32 v177, 0x82, v175
	v_cmp_lt_u32_e32 vcc, v177, v176
	s_nop 1
	v_cndmask_b32_e32 v97, v213, v98, vcc
	v_add_u32_e32 v177, 0x83, v175
	v_cmp_lt_u32_e32 vcc, v177, v176
	s_nop 1
	v_cndmask_b32_e32 v99, v213, v99, vcc
	v_add_u32_e32 v177, 0x90, v175
	v_cmp_lt_u32_e32 vcc, v177, v176
	s_nop 1
	v_cndmask_b32_e32 v129, v213, v88, vcc
	v_max3_f32 v106, v106, v127, v100
	v_add_u32_e32 v177, 0x91, v175
	v_cmp_lt_u32_e32 vcc, v177, v176
	s_nop 1
	v_cndmask_b32_e32 v98, v213, v89, vcc
	v_max3_f32 v106, v106, v101, v102
	v_max3_f32 v106, v106, v103, v96
	v_max3_f32 v106, v106, v97, v99
	v_add_u32_e32 v177, 0x92, v175
	v_cmp_lt_u32_e32 vcc, v177, v176
	s_nop 1
	v_cndmask_b32_e32 v90, v213, v90, vcc
	v_max3_f32 v88, v106, v129, v98
	v_add_u32_e32 v177, 0x93, v175
	v_cmp_lt_u32_e32 vcc, v177, v176
	s_nop 1
	v_cndmask_b32_e32 v89, v213, v91, vcc
	v_cmp_lt_i32_e32 vcc, v209, v210
	v_max3_f32 v91, v88, v90, v89
	s_nop 0
	v_cndmask_b32_e32 v88, v208, v209, vcc
	v_lshlrev_b32_e32 v88, 2, v88
	ds_bpermute_b32 v106, v88, v91
	v_cmp_lt_i32_e32 vcc, v211, v210
	s_waitcnt lgkmcnt(0)
	v_max_f32_e32 v106, v106, v106
	v_max_f32_e32 v91, v91, v106
	v_cndmask_b32_e32 v106, v208, v211, vcc
	v_lshlrev_b32_e32 v131, 2, v106
	ds_bpermute_b32 v106, v131, v91
	s_waitcnt lgkmcnt(0)
	v_max_f32_e32 v106, v106, v106
	v_max_f32_e32 v106, v91, v106
	s_mov_b32 s100, 0x3fb8aa3b
	v_mul_f32_e32 v177, 0xbfb8aa3b, v106
	v_fma_f32 v3, v3, s100, v177
	v_fma_f32 v2, v2, s100, v177
	v_exp_f32_e32 v3, v3
	v_exp_f32_e32 v135, v2
	v_fma_f32 v94, v94, s100, v177
	v_add_f32_e32 v91, 0, v3
	v_add_f32_e32 v2, v135, v91
	v_fma_f32 v91, v92, s100, v177
	v_fma_f32 v92, v93, s100, v177
	v_exp_f32_e32 v91, v91
	v_fma_f32 v93, v95, s100, v177
	v_exp_f32_e32 v92, v92
	v_exp_f32_e32 v93, v93
	v_fma_f32 v95, v124, s100, v177
	v_exp_f32_e32 v94, v94
	v_fma_f32 v124, v125, s100, v177
	v_add_f32_e32 v2, v91, v2
	v_exp_f32_e32 v95, v95
	v_fma_f32 v125, v126, s100, v177
	v_add_f32_e32 v2, v92, v2
	v_exp_f32_e32 v124, v124
	v_fma_f32 v120, v120, s100, v177
	v_add_f32_e32 v2, v93, v2
	v_exp_f32_e32 v125, v125
	v_fma_f32 v121, v121, s100, v177
	v_add_f32_e32 v2, v94, v2
	v_exp_f32_e32 v120, v120
	v_fma_f32 v122, v122, s100, v177
	v_add_f32_e32 v2, v95, v2
	v_exp_f32_e32 v121, v121
	v_fma_f32 v123, v123, s100, v177
	v_add_f32_e32 v2, v124, v2
	v_exp_f32_e32 v122, v122
	v_fma_f32 v116, v116, s100, v177
	v_add_f32_e32 v2, v125, v2
	v_exp_f32_e32 v123, v123
	v_fma_f32 v117, v117, s100, v177
	v_fma_f32 v112, v112, s100, v177
	v_add_f32_e32 v2, v120, v2
	v_exp_f32_e32 v116, v116
	v_fma_f32 v118, v118, s100, v177
	v_add_f32_e32 v2, v121, v2
	v_exp_f32_e32 v117, v117
	v_fma_f32 v119, v119, s100, v177
	v_exp_f32_e32 v126, v112
	v_fma_f32 v112, v113, s100, v177
	v_add_f32_e32 v2, v122, v2
	v_exp_f32_e32 v118, v118
	v_add_f32_e32 v2, v123, v2
	v_exp_f32_e32 v119, v119
	v_exp_f32_e32 v152, v112
	v_fma_f32 v112, v114, s100, v177
	v_fma_f32 v108, v108, s100, v177
	v_add_f32_e32 v2, v116, v2
	v_add_f32_e32 v2, v117, v2
	v_exp_f32_e32 v153, v112
	v_fma_f32 v112, v115, s100, v177
	v_exp_f32_e32 v155, v108
	v_fma_f32 v108, v109, s100, v177
	v_add_f32_e32 v2, v118, v2
	v_add_f32_e32 v2, v119, v2
	v_exp_f32_e32 v154, v112
	v_exp_f32_e32 v160, v108
	v_fma_f32 v108, v110, s100, v177
	v_add_f32_e32 v2, v126, v2
	v_add_f32_e32 v2, v152, v2
	v_exp_f32_e32 v161, v108
	v_fma_f32 v108, v111, s100, v177
	v_add_f32_e32 v2, v153, v2
	v_fma_f32 v104, v104, s100, v177
	v_add_f32_e32 v2, v154, v2
	v_exp_f32_e32 v162, v108
	v_fma_f32 v105, v105, s100, v177
	v_fma_f32 v100, v100, s100, v177
	v_add_f32_e32 v2, v155, v2
	v_exp_f32_e32 v104, v104
	v_fma_f32 v107, v107, s100, v177
	v_add_f32_e32 v2, v160, v2
	v_exp_f32_e32 v105, v105
	v_fma_f32 v108, v127, s100, v177
	v_exp_f32_e32 v163, v100
	v_fma_f32 v100, v101, s100, v177
	v_add_f32_e32 v2, v161, v2
	v_exp_f32_e32 v107, v107
	v_fma_f32 v96, v96, s100, v177
	v_add_f32_e32 v2, v162, v2
	v_exp_f32_e32 v127, v108
	v_exp_f32_e32 v165, v100
	v_fma_f32 v100, v102, s100, v177
	v_add_f32_e32 v2, v104, v2
	v_exp_f32_e32 v168, v96
	v_fma_f32 v96, v97, s100, v177
	v_add_f32_e32 v2, v105, v2
	v_exp_f32_e32 v166, v100
	v_fma_f32 v100, v103, s100, v177
	v_add_f32_e32 v2, v107, v2
	v_exp_f32_e32 v169, v96
	v_fma_f32 v96, v99, s100, v177
	v_add_f32_e32 v2, v127, v2
	v_exp_f32_e32 v167, v100
	v_add_f32_e32 v2, v163, v2
	v_exp_f32_e32 v170, v96
	v_fma_f32 v96, v129, s100, v177
	v_add_f32_e32 v2, v165, v2
	v_add_f32_e32 v2, v166, v2
	v_exp_f32_e32 v129, v96
	v_fma_f32 v96, v98, s100, v177
	v_add_f32_e32 v2, v167, v2
	v_fma_f32 v90, v90, s100, v177
	v_add_f32_e32 v2, v168, v2
	v_exp_f32_e32 v171, v96
	v_fma_f32 v89, v89, s100, v177
	v_add_f32_e32 v2, v169, v2
	v_exp_f32_e32 v172, v90
	v_add_f32_e32 v2, v170, v2
	v_exp_f32_e32 v173, v89
	v_add_f32_e32 v2, v129, v2
	v_add_f32_e32 v2, v171, v2
	v_add_f32_e32 v2, v172, v2
	v_add_f32_e32 v2, v173, v2
	ds_bpermute_b32 v88, v88, v2
	v_cvt_pk_bf16_f32 v89, v91, v92
	v_cvt_pk_bf16_f32 v90, v93, v94
	v_cvt_pk_bf16_f32 v91, v95, v124
	v_add_u32_e32 v178, 0x2000, v151
	v_add_u32_e32 v179, 0x4000, v151
	v_add_u32_e32 v180, 0x6000, v151
	ds_read2_b64 v[216:219], v151 offset1:4
	ds_read2_b64 v[220:223], v178 offset0:68 offset1:72
	ds_read2_b64 v[224:227], v179 offset0:136 offset1:140
	ds_read2_b64 v[228:231], v180 offset0:204 offset1:208
	ds_read2_b64 v[232:235], v151 offset0:8 offset1:12
	ds_read2_b64 v[236:239], v178 offset0:76 offset1:80
	ds_read2_b64 v[240:243], v179 offset0:144 offset1:148
	ds_read2_b64 v[244:247], v180 offset0:212 offset1:216
	ds_read2_b64 v[182:185], v151 offset0:16 offset1:20
	ds_read2_b64 v[186:189], v178 offset0:84 offset1:88
	ds_read2_b64 v[190:193], v179 offset0:152 offset1:156
	ds_read2_b64 v[194:197], v180 offset0:220 offset1:224
	s_waitcnt lgkmcnt(12)
	v_add_f32_e32 v174, v2, v88
	v_add_u32_e32 v2, s71, v0
	v_cvt_pk_bf16_f32 v88, v3, v135
	v_add_u32_e32 v0, 0x2000, v151
	v_add_u32_e32 v3, 0x4000, v151
	v_add_u32_e32 v124, 0x6000, v151
	ds_bpermute_b32 v131, v131, v174
	s_ashr_i32 s71, s70, 31
	v_mov_b32_e32 v135, v1
	s_waitcnt lgkmcnt(12)
	v_mfma_f32_16x16x32_bf16 v[100:103], v[216:219], v[88:91], 0
	s_waitcnt lgkmcnt(11)
	v_mfma_f32_16x16x32_bf16 v[96:99], v[220:223], v[88:91], 0
	s_waitcnt lgkmcnt(10)
	v_mfma_f32_16x16x32_bf16 v[92:95], v[224:227], v[88:91], 0
	s_waitcnt lgkmcnt(9)
	v_mfma_f32_16x16x32_bf16 v[88:91], v[228:231], v[88:91], 0
	ds_read2_b64 v[216:219], v151 offset0:24 offset1:28
	ds_read2_b64 v[220:223], v178 offset0:92 offset1:96
	ds_read2_b64 v[224:227], v179 offset0:160 offset1:164
	ds_read2_b64 v[228:231], v180 offset0:228 offset1:232
	v_cvt_pk_bf16_f32 v108, v125, v120
	v_cvt_pk_bf16_f32 v109, v121, v122
	v_cvt_pk_bf16_f32 v110, v123, v116
	v_cvt_pk_bf16_f32 v111, v117, v118
	s_waitcnt lgkmcnt(12)
	s_nop 0
	v_mfma_f32_16x16x32_bf16 v[100:103], v[232:235], v[108:111], v[100:103]
	s_waitcnt lgkmcnt(11)
	v_mfma_f32_16x16x32_bf16 v[96:99], v[236:239], v[108:111], v[96:99]
	s_waitcnt lgkmcnt(10)
	v_mfma_f32_16x16x32_bf16 v[92:95], v[240:243], v[108:111], v[92:95]
	s_waitcnt lgkmcnt(9)
	v_mfma_f32_16x16x32_bf16 v[88:91], v[244:247], v[108:111], v[88:91]
	ds_read2_b64 v[232:235], v151 offset0:32 offset1:36
	ds_read2_b64 v[236:239], v178 offset0:100 offset1:104
	ds_read2_b64 v[240:243], v179 offset0:168 offset1:172
	ds_read2_b64 v[244:247], v180 offset0:236 offset1:240
	v_cvt_pk_bf16_f32 v108, v119, v126
	v_cvt_pk_bf16_f32 v109, v152, v153
	v_cvt_pk_bf16_f32 v110, v154, v155
	v_cvt_pk_bf16_f32 v111, v160, v161
	s_waitcnt lgkmcnt(12)
	s_nop 0
	v_mfma_f32_16x16x32_bf16 v[100:103], v[182:185], v[108:111], v[100:103]
	s_waitcnt lgkmcnt(11)
	v_mfma_f32_16x16x32_bf16 v[96:99], v[186:189], v[108:111], v[96:99]
	s_waitcnt lgkmcnt(10)
	v_mfma_f32_16x16x32_bf16 v[92:95], v[190:193], v[108:111], v[92:95]
	s_waitcnt lgkmcnt(9)
	v_mfma_f32_16x16x32_bf16 v[88:91], v[194:197], v[108:111], v[88:91]
	v_cvt_pk_bf16_f32 v108, v162, v104
	v_cvt_pk_bf16_f32 v109, v105, v107
	v_cvt_pk_bf16_f32 v110, v127, v163
	v_cvt_pk_bf16_f32 v111, v165, v166
	s_waitcnt lgkmcnt(8)
	v_add_f32_e32 v107, v174, v131
	s_waitcnt lgkmcnt(7)
	s_nop 0
	v_mfma_f32_16x16x32_bf16 v[100:103], v[216:219], v[108:111], v[100:103]
	s_waitcnt lgkmcnt(6)
	v_mfma_f32_16x16x32_bf16 v[96:99], v[220:223], v[108:111], v[96:99]
	s_waitcnt lgkmcnt(5)
	v_mfma_f32_16x16x32_bf16 v[92:95], v[224:227], v[108:111], v[92:95]
	s_waitcnt lgkmcnt(4)
	v_mfma_f32_16x16x32_bf16 v[88:91], v[228:231], v[108:111], v[88:91]
	v_cvt_pk_bf16_f32 v108, v167, v168
	v_cvt_pk_bf16_f32 v109, v169, v170
	v_cvt_pk_bf16_f32 v110, v129, v171
	v_cvt_pk_bf16_f32 v111, v172, v173
	v_div_scale_f32 v0, s[64:65], v107, v107, 1.0
	v_rcp_f32_e32 v3, v0
	s_lshl_b64 s[64:65], s[70:71], 25
	s_waitcnt lgkmcnt(3)
	s_nop 0
	v_mfma_f32_16x16x32_bf16 v[100:103], v[232:235], v[108:111], v[100:103]
	s_waitcnt lgkmcnt(2)
	v_mfma_f32_16x16x32_bf16 v[96:99], v[236:239], v[108:111], v[96:99]
	s_waitcnt lgkmcnt(1)
	v_mfma_f32_16x16x32_bf16 v[92:95], v[240:243], v[108:111], v[92:95]
	s_waitcnt lgkmcnt(0)
	v_mfma_f32_16x16x32_bf16 v[88:91], v[244:247], v[108:111], v[88:91]
	v_fma_f32 v104, -v0, v3, 1.0
	v_fmac_f32_e32 v3, v104, v3
	v_div_scale_f32 v104, vcc, 1.0, v107, 1.0
	v_mul_f32_e32 v105, v104, v3
	v_fma_f32 v108, -v0, v105, v104
	v_fmac_f32_e32 v105, v108, v3
	v_fma_f32 v0, -v0, v105, v104
	v_div_fmas_f32 v0, v0, v3, v105
	s_add_u32 s64, s52, s64
	v_ashrrev_i32_e32 v3, 31, v2
	s_addc_u32 s65, s53, s65
	v_lshlrev_b64 v[104:105], 11, v[2:3]
	v_div_fixup_f32 v0, v0, v107, 1.0
	v_lshl_add_u64 v[104:105], s[64:65], 0, v[104:105]
	s_lshl_b32 s72, s79, 7
	v_lshl_add_u64 v[104:105], v[104:105], 0, s[72:73]
	v_pk_mul_f32 v[100:101], v[0:1], v[100:101] op_sel_hi:[0,1]
	v_pk_mul_f32 v[102:103], v[0:1], v[102:103] op_sel_hi:[0,1]
	v_pk_mul_f32 v[96:97], v[0:1], v[96:97] op_sel_hi:[0,1]
	v_pk_mul_f32 v[98:99], v[0:1], v[98:99] op_sel_hi:[0,1]
	v_pk_mul_f32 v[92:93], v[0:1], v[92:93] op_sel_hi:[0,1]
	v_pk_mul_f32 v[94:95], v[0:1], v[94:95] op_sel_hi:[0,1]
	v_pk_mul_f32 v[88:89], v[0:1], v[88:89] op_sel_hi:[0,1]
	v_pk_mul_f32 v[90:91], v[0:1], v[90:91] op_sel_hi:[0,1]
	v_lshl_add_u64 v[104:105], v[104:105], 0, v[134:135]
	v_cvt_pk_bf16_f32 v100, v100, v101
	v_cvt_pk_bf16_f32 v101, v102, v103
	v_cvt_pk_bf16_f32 v96, v96, v97
	v_cvt_pk_bf16_f32 v97, v98, v99
	v_cvt_pk_bf16_f32 v92, v92, v93
	v_cvt_pk_bf16_f32 v93, v94, v95
	v_cvt_pk_bf16_f32 v88, v88, v89
	v_cvt_pk_bf16_f32 v89, v90, v91
	global_store_dwordx2 v[104:105], v[100:101], off
	global_store_dwordx2 v[104:105], v[96:97], off offset:32
	global_store_dwordx2 v[104:105], v[92:93], off offset:64
	global_store_dwordx2 v[104:105], v[88:89], off offset:96
	s_mov_b64 s[64:65], exec
	v_readlane_b32 s68, v255, 11
	v_readlane_b32 s69, v255, 12
	s_and_b64 s[68:69], s[64:65], s[68:69]
	s_mov_b64 exec, s[68:69]
	s_cbranch_execz .LBB0_749
	s_mov_b32 s68, 0x800000
	v_cmp_gt_f32_e32 vcc, s68, v107
	s_mov_b32 s68, 0x3f317217
	v_lshlrev_b64 v[2:3], 6, v[2:3]
	v_cndmask_b32_e64 v0, 0, 32, vcc
	v_ldexp_f32 v0, v107, v0
	v_log_f32_e32 v0, v0
	v_cndmask_b32_e32 v88, 0, v212, vcc
	v_mul_f32_e32 v89, 0x3f317217, v0
	v_fma_f32 v89, v0, s68, -v89
	s_mov_b32 s68, 0x7f800000
	v_fmac_f32_e32 v89, 0x3377d1cf, v0
	v_cmp_lt_f32_e64 vcc, |v0|, s68
	s_lshl_b64 s[68:69], s[70:71], 20
	v_fmac_f32_e32 v89, 0x3f317217, v0
	s_add_u32 s68, s55, s68
	v_readlane_b32 s70, v254, 44
	v_cndmask_b32_e32 v0, v0, v89, vcc
	s_addc_u32 s69, s70, s69
	v_sub_f32_e32 v0, v0, v88
	v_lshl_add_u64 v[2:3], s[68:69], 0, v[2:3]
	s_lshl_b32 s72, s79, 2
	v_add_f32_e32 v0, v106, v0
	v_lshl_add_u64 v[2:3], v[2:3], 0, s[72:73]
	global_store_dword v[2:3], v0, off
	s_branch .LBB0_749
